# deferred-prep table v12: as v10, and in the L0 w_out idle window the adaLN items are nobody's fifth item (transposes last)
# baseline (speedup 1.0000x reference)
; __device__ void phase_prep(const Params& p, LAS unsigned char* lds) {
;     ...
;     constexpr int T_IN = 16 * 17, T_BA = 8 * 4, T_WO = 16 * 4, T_UP = 16 * 22, T_DN = 44 * 4, T_L = T_IN + T_BA + T_WO + T_UP + T_DN;
;     constexpr int I_TR = 2 * T_L, I_POOL = I_TR + 128, I_FOUR = I_POOL + 256, I_MOD = I_FOUR + 192, I_ALL = I_MOD + 1;
;     for (int prep_rep = 0; prep_rep < ((PROBE >= 301 && PROBE <= 304) ? 2 : 1); ++prep_rep)
;     for (int it = blockIdx.x; it < I_ALL; it += gridDim.x) {
;     ...
;         if (prep_rep == 1) { const int cls = (it < I_TR) ? 301 : (it < I_FOUR) ? 302 : (it < I_MOD) ? 303 : 304; if (cls != PROBE) continue; }
;     ...
;         if (it < I_TR) {
.Lmy_dp_m1:
	s_cmp_lt_u32 s26, 16
	s_cbranch_scc1 .LBB0_735
	s_sub_i32 s0, s26, 16
	v_writelane_b32 v252, s0, 1
	s_movk_i32 s1, 240
	v_writelane_b32 v252, s1, 2
	s_movk_i32 s1, 992
	v_writelane_b32 v252, s1, 3
	s_movk_i32 s1, 368
	v_writelane_b32 v252, s1, 0
	s_movk_i32 s1, 864
	v_writelane_b32 v252, s1, 5
	s_movk_i32 s1, 1408
	v_writelane_b32 v252, s1, 6
	s_movk_i32 s1, 960
	v_writelane_b32 v252, s1, 7
	s_movk_i32 s1, 272
	v_writelane_b32 v252, s1, 8
	s_movk_i32 s1, 32767
	v_writelane_b32 v252, s1, 9
	s_movk_i32 s1, 0
	v_writelane_b32 v252, s1, 10
	s_branch .LBB0_650
